# conformer conv: the 31 per-tap weight loads (one exposed global round trip each) replaced by one LDS-DMA of the tap table + ds_read per tap
# speedup vs baseline: 1.0100x; 1.0052x over previous
; #define LAS __attribute__((address_space(3)))
; #define SG(x) __builtin_amdgcn_rcpf(1.f + __builtin_amdgcn_exp2f((x) * -1.4426950408889634f))
; __device__ void conv_unit(LAS unsigned char* lds, const bf16_t* __restrict__ Z, bf16_t* __restrict__ MIX, int unit,
;                           const float* __restrict__ ccw, const float* __restrict__ ccb, const float* __restrict__ lng, const float* __restrict__ lnb, const float* __restrict__ scw) {
;     ...
;     { u32x4 cav[6], cgv[6];
; #pragma unroll
;       for (int i = 0; i < 6; ++i) { const int id = tid + 512 * i, row = id >> 5, c8 = (id & 31) * 8; int gr = t0 - 30 + row; gr = gr < 0 ? 0 : gr; gr = gr > MTOK - 1 ? MTOK - 1 : gr;
;           const bf16_t* zr = Z + (size_t)gr * DIN + 1536 + c8; cav[i] = *(const u32x4*)zr; cgv[i] = *(const u32x4*)(zr + 256); }
; #pragma unroll
;       for (int i = 0; i < 6; ++i) { const int id = tid + 512 * i, row = id >> 5, c8 = (id & 31) * 8, tp = tpos0 - 30 + row; const u32x4 ca = cav[i], cg = cgv[i];
;           f32x4 a, b;
;           a[0] = bflo(ca.x) * SG(bflo(cg.x)); a[1] = bfhi(ca.x) * SG(bfhi(cg.x)); a[2] = bflo(ca.y) * SG(bflo(cg.y)); a[3] = bfhi(ca.y) * SG(bfhi(cg.y));
;           b[0] = bflo(ca.z) * SG(bflo(cg.z)); b[1] = bfhi(ca.z) * SG(bfhi(cg.z)); b[2] = bflo(ca.w) * SG(bflo(cg.w)); b[3] = bfhi(ca.w) * SG(bfhi(cg.w));
;           if (tp < 0) { a = (f32x4){0.f, 0.f, 0.f, 0.f}; b = a; }
;           if (id < 94 * 32) { *(LAS f32x4*)(ub + row * 256 + c8) = a; *(LAS f32x4*)(ub + row * 256 + c8 + 4) = b; } } }
.LBB0_127:
	v_mov_b32_e32 v100, v187
	s_lshl_b32 s17, s16, 6
	v_lshlrev_b32_e32 v0, 3, v100
	v_and_b32_e32 v101, 0xf8, v0
	v_add_u32_e32 v0, 0x200, v100
	s_sub_i32 s14, s17, 30
	v_ashrrev_i32_e32 v51, 5, v0
	v_add_u32_e32 v0, s14, v51
	v_med3_i32 v0, v0, 0, v194
	v_readlane_b32 s10, v252, 20
	v_mul_u32_u24_e32 v0, 0xb00, v0
	v_readlane_b32 s11, v252, 21
	s_waitcnt lgkmcnt(0)
	s_barrier
	v_and_b32_e32 v2, 63, v187
	v_lshrrev_b32_e32 v3, 6, v187
	v_lshlrev_b32_e32 v2, 4, v2
	v_lshl_or_b32 v2, v3, 12, v2
	v_add_u32_e32 v2, 0xfffffc00, v2
	v_ashrrev_i32_e32 v3, 31, v2
	v_readfirstlane_b32 s3, v187
	v_lshl_add_u64 v[2:3], s[42:43], 0, v[2:3]
	s_lshr_b32 s3, s3, 6
	s_lshl_b32 s3, s3, 12
	s_add_i32 s3, s3, 0x18000
	s_mov_b32 m0, s3
	s_nop 0
	global_load_lds_dwordx4 v[2:3], off
	global_load_lds_dwordx4 v[2:3], off offset:1024
	global_load_lds_dwordx4 v[2:3], off offset:2048
	s_cmp_eq_u32 s3, 0x1f000
	s_cbranch_scc1 .Lcv_tap_done
	global_load_lds_dwordx4 v[2:3], off offset:3072
.Lcv_tap_done:
	v_lshl_add_u64 v[2:3], v[0:1], 1, s[10:11]
	v_lshlrev_b32_e32 v0, 1, v101
	v_lshl_add_u64 v[2:3], v[2:3], 0, v[0:1]
	global_load_dwordx4 v[34:37], v[2:3], off offset:3072
	global_load_dwordx4 v[38:41], v[2:3], off offset:3584
	v_add_u32_e32 v2, 0x400, v100
	v_ashrrev_i32_e32 v50, 5, v2
	v_add_u32_e32 v2, s14, v50
	v_med3_i32 v2, v2, 0, v194
	v_mul_u32_u24_e32 v2, 0xb00, v2
	v_mov_b32_e32 v3, v1
	v_lshl_add_u64 v[2:3], v[2:3], 1, s[10:11]
	v_lshl_add_u64 v[2:3], v[2:3], 0, v[0:1]
	global_load_dwordx4 v[26:29], v[2:3], off offset:3072
	global_load_dwordx4 v[30:33], v[2:3], off offset:3584
	v_add_u32_e32 v2, 0x600, v100
	v_ashrrev_i32_e32 v49, 5, v2
	v_add_u32_e32 v2, s14, v49
	v_med3_i32 v2, v2, 0, v194
	v_mul_u32_u24_e32 v2, 0xb00, v2
	v_mov_b32_e32 v3, v1
	v_lshl_add_u64 v[2:3], v[2:3], 1, s[10:11]
	v_lshl_add_u64 v[2:3], v[2:3], 0, v[0:1]
	global_load_dwordx4 v[18:21], v[2:3], off offset:3072
	global_load_dwordx4 v[22:25], v[2:3], off offset:3584
	v_add_u32_e32 v2, 0x800, v100
	v_ashrrev_i32_e32 v48, 5, v2
	v_add_u32_e32 v2, s14, v48
	v_med3_i32 v2, v2, 0, v194
	v_mul_u32_u24_e32 v2, 0xb00, v2
	v_mov_b32_e32 v3, v1
	v_lshl_add_u64 v[2:3], v[2:3], 1, s[10:11]
	v_lshl_add_u64 v[2:3], v[2:3], 0, v[0:1]
	global_load_dwordx4 v[10:13], v[2:3], off offset:3072
	global_load_dwordx4 v[14:17], v[2:3], off offset:3584
	v_add_u32_e32 v2, 0xa00, v100
	v_ashrrev_i32_e32 v46, 5, v2
	v_add_u32_e32 v2, s14, v46
	v_med3_i32 v2, v2, 0, v194
	v_mul_u32_u24_e32 v2, 0xb00, v2
	v_mov_b32_e32 v3, v1
	v_lshl_add_u64 v[2:3], v[2:3], 1, s[10:11]
	v_lshl_add_u64 v[6:7], v[2:3], 0, v[0:1]
	global_load_dwordx4 v[2:5], v[6:7], off offset:3072
	s_nop 0
	global_load_dwordx4 v[6:9], v[6:7], off offset:3584
	s_and_b32 s18, s17, 0xfc0
	s_movk_i32 s10, 0xbc0
	v_lshl_add_u32 v47, v101, 2, 0
	s_sub_i32 s3, 30, s18
	v_cmp_gt_i32_e32 vcc, s10, v100
	s_and_saveexec_b64 s[10:11], vcc
	s_cbranch_execz .LBB0_129
	v_ashrrev_i32_e32 v44, 5, v100
	v_add_u32_e32 v42, s14, v44
	v_max_i32_e32 v42, 0, v42
	s_movk_i32 s14, 0xb00
	v_mul_lo_u32 v42, v42, s14
	v_readlane_b32 s14, v252, 20
	v_mov_b32_e32 v43, v1
	v_readlane_b32 s15, v252, 21
	v_lshl_add_u32 v60, v44, 10, v47
	v_cmp_gt_i32_e32 vcc, s3, v44
	v_lshl_add_u64 v[42:43], v[42:43], 1, s[14:15]
	v_lshl_add_u64 v[42:43], v[42:43], 0, v[0:1]
	global_load_dwordx4 v[52:55], v[42:43], off offset:3584
	global_load_dwordx4 v[56:59], v[42:43], off offset:3072
	s_waitcnt vmcnt(1)
	v_lshlrev_b32_e32 v42, 16, v52
	v_and_b32_e32 v43, 0xffff0000, v52
	v_mul_f32_e32 v42, 0xbfb8aa3b, v42
	v_mul_f32_e32 v43, 0xbfb8aa3b, v43
	v_exp_f32_e32 v42, v42
	v_exp_f32_e32 v43, v43
	s_waitcnt vmcnt(0)
	v_lshlrev_b32_e32 v44, 16, v56
	v_and_b32_e32 v45, 0xffff0000, v56
	v_add_f32_e32 v42, 1.0, v42
	v_add_f32_e32 v43, 1.0, v43
	v_rcp_f32_e32 v42, v42
	v_rcp_f32_e32 v43, v43
	v_lshlrev_b32_e32 v52, 16, v57
	v_lshlrev_b32_e32 v56, 16, v58
	v_pk_mul_f32 v[42:43], v[42:43], v[44:45]
	v_lshlrev_b32_e32 v44, 16, v53
	v_and_b32_e32 v45, 0xffff0000, v53
	v_mul_f32_e32 v44, 0xbfb8aa3b, v44
	v_mul_f32_e32 v45, 0xbfb8aa3b, v45
	v_exp_f32_e32 v44, v44
	v_exp_f32_e32 v45, v45
	v_and_b32_e32 v53, 0xffff0000, v57
	v_and_b32_e32 v57, 0xffff0000, v58
	v_add_f32_e32 v44, 1.0, v44
	v_add_f32_e32 v45, 1.0, v45
	v_rcp_f32_e32 v44, v44
	v_rcp_f32_e32 v45, v45
	v_cndmask_b32_e64 v43, v43, 0, vcc
	v_cndmask_b32_e64 v42, v42, 0, vcc
	v_pk_mul_f32 v[44:45], v[44:45], v[52:53]
	v_lshlrev_b32_e32 v52, 16, v54
	v_and_b32_e32 v53, 0xffff0000, v54
	v_mul_f32_e32 v52, 0xbfb8aa3b, v52
	v_mul_f32_e32 v53, 0xbfb8aa3b, v53
	v_lshlrev_b32_e32 v54, 16, v55
	v_and_b32_e32 v55, 0xffff0000, v55
	v_exp_f32_e32 v52, v52
	v_exp_f32_e32 v53, v53
	v_mul_f32_e32 v54, 0xbfb8aa3b, v54
	v_mul_f32_e32 v55, 0xbfb8aa3b, v55
	v_exp_f32_e32 v54, v54
	v_exp_f32_e32 v55, v55
	v_add_f32_e32 v52, 1.0, v52
	v_add_f32_e32 v53, 1.0, v53
	v_rcp_f32_e32 v52, v52
	v_rcp_f32_e32 v53, v53
	v_add_f32_e32 v54, 1.0, v54
	v_add_f32_e32 v55, 1.0, v55
	v_rcp_f32_e32 v54, v54
	v_rcp_f32_e32 v55, v55
	v_pk_mul_f32 v[52:53], v[52:53], v[56:57]
	v_lshlrev_b32_e32 v56, 16, v59
	v_and_b32_e32 v57, 0xffff0000, v59
	v_cndmask_b32_e64 v45, v45, 0, vcc
	v_cndmask_b32_e64 v44, v44, 0, vcc
	v_pk_mul_f32 v[54:55], v[54:55], v[56:57]
	v_cndmask_b32_e64 v53, v53, 0, vcc
	v_cndmask_b32_e64 v55, v55, 0, vcc
	v_cndmask_b32_e64 v54, v54, 0, vcc
	v_cndmask_b32_e64 v52, v52, 0, vcc
	ds_write_b128 v60, v[42:45]
	ds_write_b128 v60, v[52:55] offset:16

; __device__ void conv_unit(LAS unsigned char* lds, const bf16_t* __restrict__ Z, bf16_t* __restrict__ MIX, int unit,
;                           const float* __restrict__ ccw, const float* __restrict__ ccb, const float* __restrict__ lng, const float* __restrict__ lnb, const float* __restrict__ scw) {
;     ...
;     { const int ch = tid & 255, half = tid >> 8; float acc[32]; const float bias = ccb[ch];
; #pragma unroll
;       for (int j = 0; j < 32; ++j) acc[j] = bias;
.LBB0_139:
	s_or_b64 exec, exec, s[10:11]
	v_lshlrev_b32_e32 v102, 2, v100
	s_waitcnt vmcnt(1)
	v_and_b32_e32 v2, 0x3fc, v102
	s_waitcnt lgkmcnt(0)
	s_barrier
	global_load_dword v68, v2, s[0:1]
	v_lshlrev_b32_e32 v4, 7, v100
	v_mov_b32_e32 v3, v1
	v_and_b32_e32 v4, 0xffff8000, v4
	s_mov_b32 s3, 0
	v_add3_u32 v103, 0, v4, v2
	v_add_u32_e32 v2, 0x18000, v2
	s_waitcnt vmcnt(0)
	v_mov_b32_e32 v69, v68
	v_mov_b32_e32 v76, v68
	v_mov_b32_e32 v77, v68
	v_mov_b32_e32 v78, v68
	v_mov_b32_e32 v79, v68
	v_mov_b32_e32 v80, v68
	v_mov_b32_e32 v81, v68
	v_mov_b32_e32 v82, v68
	v_mov_b32_e32 v83, v68
	v_mov_b32_e32 v84, v68
	v_mov_b32_e32 v85, v68
	v_mov_b32_e32 v86, v68
	v_mov_b32_e32 v87, v68
	v_mov_b32_e32 v88, v68
	v_mov_b32_e32 v89, v68
	v_mov_b32_e32 v90, v68
	v_mov_b32_e32 v91, v68
	v_mov_b32_e32 v92, v68
	v_mov_b32_e32 v93, v68
	v_mov_b32_e32 v94, v68
	v_mov_b32_e32 v95, v68
	v_mov_b32_e32 v96, v68
	v_mov_b32_e32 v97, v68
	v_mov_b32_e32 v98, v68
	v_mov_b32_e32 v99, v68
	v_mov_b32_e32 v74, v68
	v_mov_b32_e32 v75, v68
	v_mov_b32_e32 v72, v68
	v_mov_b32_e32 v73, v68
	v_mov_b32_e32 v70, v68
	v_mov_b32_e32 v71, v68
	s_branch .LBB0_141

; #define LAS __attribute__((address_space(3)))
; __device__ void conv_unit(LAS unsigned char* lds, const bf16_t* __restrict__ Z, bf16_t* __restrict__ MIX, int unit,
;                           const float* __restrict__ ccw, const float* __restrict__ ccb, const float* __restrict__ lng, const float* __restrict__ lnb, const float* __restrict__ scw) {
;     ...
;       for (int k = 0; k < 31; ++k) { const float w = ccw[k * 256 + ch]; LAS const float* up = ub + (half * 32 + k) * 256 + ch;
; #pragma unroll
;           for (int j = 0; j < 32; ++j) acc[j] = __builtin_fmaf(w, up[j * 256], acc[j]); }
.LBB0_141:
	v_add_u32_e32 v3, s3, v2
	s_nop 0
	ds_read_b32 v34, v3
	v_add_u32_e32 v104, s3, v103
	ds_read2st64_b32 v[36:37], v104 offset1:4
	ds_read2st64_b32 v[38:39], v104 offset0:8 offset1:12
	ds_read2st64_b32 v[40:41], v104 offset0:16 offset1:20
	ds_read2st64_b32 v[42:43], v104 offset0:24 offset1:28
	ds_read2st64_b32 v[44:45], v104 offset0:32 offset1:36
	ds_read2st64_b32 v[46:47], v104 offset0:40 offset1:44
	ds_read2st64_b32 v[48:49], v104 offset0:48 offset1:52
	ds_read2st64_b32 v[50:51], v104 offset0:56 offset1:60
	ds_read2st64_b32 v[52:53], v104 offset0:64 offset1:68
	ds_read2st64_b32 v[54:55], v104 offset0:72 offset1:76
	ds_read2st64_b32 v[56:57], v104 offset0:80 offset1:84
	ds_read2st64_b32 v[58:59], v104 offset0:88 offset1:92
	ds_read2st64_b32 v[60:61], v104 offset0:96 offset1:100
	ds_read2st64_b32 v[66:67], v104 offset0:104 offset1:108
	ds_read2st64_b32 v[64:65], v104 offset0:112 offset1:116
	ds_read2st64_b32 v[62:63], v104 offset0:120 offset1:124
	s_waitcnt lgkmcnt(14)
	v_mov_b32_e32 v4, v37
	v_mov_b32_e32 v5, v36
	v_mov_b32_e32 v6, v39
	v_mov_b32_e32 v7, v38
	s_waitcnt lgkmcnt(13)
	v_mov_b32_e32 v8, v41
	v_mov_b32_e32 v9, v40
	s_waitcnt lgkmcnt(12)
	v_mov_b32_e32 v10, v43
	v_mov_b32_e32 v11, v42
	s_waitcnt lgkmcnt(11)
	v_mov_b32_e32 v12, v45
	v_mov_b32_e32 v13, v44
	s_waitcnt lgkmcnt(10)
	v_mov_b32_e32 v14, v47
	v_mov_b32_e32 v15, v46
	s_waitcnt lgkmcnt(9)
	v_mov_b32_e32 v16, v49
	v_mov_b32_e32 v17, v48
	s_waitcnt lgkmcnt(8)
	v_mov_b32_e32 v18, v51
	v_mov_b32_e32 v19, v50
	s_waitcnt lgkmcnt(7)
	v_mov_b32_e32 v20, v53
	v_mov_b32_e32 v21, v52
	s_waitcnt lgkmcnt(6)
	v_mov_b32_e32 v22, v55
	v_mov_b32_e32 v23, v54
	s_waitcnt lgkmcnt(5)
	v_mov_b32_e32 v24, v57
	v_mov_b32_e32 v25, v56
	s_waitcnt lgkmcnt(4)
	v_mov_b32_e32 v26, v59
	v_mov_b32_e32 v27, v58
	s_waitcnt lgkmcnt(3)
	v_mov_b32_e32 v28, v61
	v_mov_b32_e32 v29, v60
	s_mov_b64 s[10:11], -1
	s_cmpk_eq_i32 s3, 0x7800
	v_pk_fma_f32 v[4:5], v[34:35], v[4:5], v[98:99] op_sel_hi:[0,1,1]
	v_pk_fma_f32 v[6:7], v[34:35], v[6:7], v[96:97] op_sel_hi:[0,1,1]
	v_pk_fma_f32 v[8:9], v[34:35], v[8:9], v[94:95] op_sel_hi:[0,1,1]
	v_pk_fma_f32 v[10:11], v[34:35], v[10:11], v[92:93] op_sel_hi:[0,1,1]
	v_pk_fma_f32 v[12:13], v[34:35], v[12:13], v[90:91] op_sel_hi:[0,1,1]
	v_pk_fma_f32 v[14:15], v[34:35], v[14:15], v[88:89] op_sel_hi:[0,1,1]
	v_pk_fma_f32 v[16:17], v[34:35], v[16:17], v[86:87] op_sel_hi:[0,1,1]
	v_pk_fma_f32 v[18:19], v[34:35], v[18:19], v[84:85] op_sel_hi:[0,1,1]
	v_pk_fma_f32 v[20:21], v[34:35], v[20:21], v[82:83] op_sel_hi:[0,1,1]
	v_pk_fma_f32 v[22:23], v[34:35], v[22:23], v[80:81] op_sel_hi:[0,1,1]
	v_pk_fma_f32 v[24:25], v[34:35], v[24:25], v[78:79] op_sel_hi:[0,1,1]
	v_pk_fma_f32 v[26:27], v[34:35], v[26:27], v[76:77] op_sel_hi:[0,1,1]
	v_pk_fma_f32 v[28:29], v[34:35], v[28:29], v[68:69] op_sel_hi:[0,1,1]
	s_waitcnt lgkmcnt(2)
	v_pk_fma_f32 v[30:31], v[34:35], v[66:67], v[74:75] op_sel_hi:[0,1,1]
	s_waitcnt lgkmcnt(1)
	v_pk_fma_f32 v[32:33], v[34:35], v[64:65], v[72:73] op_sel_hi:[0,1,1]
	s_waitcnt lgkmcnt(0)
	v_pk_fma_f32 v[34:35], v[34:35], v[62:63], v[70:71] op_sel_hi:[0,1,1]
	s_cbranch_scc1 .LBB0_140
	ds_read_b32 v70, v3 offset:1024
	ds_read_b32 v105, v104 offset:32768
	v_mov_b32_e32 v36, v38
	v_mov_b32_e32 v38, v40
	v_mov_b32_e32 v40, v42
	v_mov_b32_e32 v42, v44
	v_mov_b32_e32 v44, v46
	v_mov_b32_e32 v46, v48
	v_mov_b32_e32 v48, v50
	v_mov_b32_e32 v50, v52
	v_mov_b32_e32 v52, v54
	v_mov_b32_e32 v54, v56
	v_mov_b32_e32 v56, v58
	v_mov_b32_e32 v58, v60
	v_mov_b32_e32 v60, v66
	v_mov_b32_e32 v66, v67
	v_mov_b32_e32 v67, v64
	v_mov_b32_e32 v64, v65
	v_mov_b32_e32 v65, v62
	v_mov_b32_e32 v104, v63
	s_mov_b64 s[10:11], 0x800
	s_addk_i32 s3, 0x800
	s_mov_b64 s[10:11], 0
	s_waitcnt lgkmcnt(1)
	v_pk_fma_f32 v[98:99], v[70:71], v[36:37], v[4:5] op_sel_hi:[0,1,1]
	v_pk_fma_f32 v[96:97], v[70:71], v[38:39], v[6:7] op_sel_hi:[0,1,1]
	v_pk_fma_f32 v[94:95], v[70:71], v[40:41], v[8:9] op_sel_hi:[0,1,1]
	v_pk_fma_f32 v[92:93], v[70:71], v[42:43], v[10:11] op_sel_hi:[0,1,1]
	v_pk_fma_f32 v[90:91], v[70:71], v[44:45], v[12:13] op_sel_hi:[0,1,1]
	v_pk_fma_f32 v[88:89], v[70:71], v[46:47], v[14:15] op_sel_hi:[0,1,1]
	v_pk_fma_f32 v[86:87], v[70:71], v[48:49], v[16:17] op_sel_hi:[0,1,1]
	v_pk_fma_f32 v[84:85], v[70:71], v[50:51], v[18:19] op_sel_hi:[0,1,1]
	v_pk_fma_f32 v[82:83], v[70:71], v[52:53], v[20:21] op_sel_hi:[0,1,1]
	v_pk_fma_f32 v[80:81], v[70:71], v[54:55], v[22:23] op_sel_hi:[0,1,1]
	v_pk_fma_f32 v[78:79], v[70:71], v[56:57], v[24:25] op_sel_hi:[0,1,1]
	v_pk_fma_f32 v[76:77], v[70:71], v[58:59], v[26:27] op_sel_hi:[0,1,1]
	v_pk_fma_f32 v[68:69], v[70:71], v[60:61], v[28:29] op_sel_hi:[0,1,1]
	v_pk_fma_f32 v[74:75], v[70:71], v[66:67], v[30:31] op_sel_hi:[0,1,1]
	v_pk_fma_f32 v[72:73], v[70:71], v[64:65], v[32:33] op_sel_hi:[0,1,1]
	s_waitcnt lgkmcnt(0)
	v_pk_fma_f32 v[70:71], v[70:71], v[104:105], v[34:35] op_sel_hi:[0,1,1]
	s_branch .LBB0_140
